# static priority: waves 0-3 (role A) raised to 1 for the whole P8/P9 K-loop, per-slot toggles removed
# baseline (speedup 1.0000x reference)
;     __host__ __device__ bool next(int i, Unit& u) const { const int L = i * G + c; if (L >= n) return false; u.pm = L; u.pn = L >> 2; return true; }
; #define PG8_STAGE(bufoff, gbase, voff) do { _Pragma("unroll") for (int _i = 0; _i < 2; ++_i) \
;         __builtin_amdgcn_global_load_lds((const unsigned*)((const char*)(gbase) + (voff)[_i]), (PG8_LAS unsigned*)(lds + (bufoff) + ldsw + _i * 8192), 16, 0, 0); } while (0)
; #define PG8_LDA(dst, b, h) do { _Pragma("unroll") for (int m = 0; m < 4; ++m) _Pragma("unroll") for (int k = 0; k < 2; ++k) dst[m][k] = *(const PG8_LAS bf16x8*)(lds + PG8_SA(b, h) + aoff + m * 2048 + k * 1024); } while (0)
; #define PG8_LDB(dst, b, h) do { _Pragma("unroll") for (int n = 0; n < 2; ++n) _Pragma("unroll") for (int k = 0; k < 2; ++k) dst[n][k] = *(const PG8_LAS bf16x8*)(lds + PG8_SB(b, h) + boff + n * 2048 + k * 1024); } while (0)
; #define PG8_SCHED __builtin_amdgcn_sched_barrier(0)
; template <class Epi, class Sched, bool ALIGN_EPI>
; __device__ __forceinline__ void gemm_phase(PG8_LAS unsigned char* lds, const Gemm g, const Sched& S, const Epi& E) {
;     ...
;         const bool has_next = S.next(ui + 1, nxt);
;         const size_t tail_ = has_next ? 0 : tailoff; const char* nA = (has_next ? (const char*)g.A + (size_t)nxt.pm * tstepA : cA) + (has_next ? 0 : tailoffA); const char* nB = (has_next ? (const char*)g.Bt + (size_t)nxt.pn * tstepB : cB) + tail_;
;         for (int t = 0; t < nt; t += 2) {
;             if constexpr (Epi::MIDK) { if (t == (nt >> 1)) E.midk(acc, cur, wr, fr); }
;             const bool last = (t == nt - 2);
;             const char* a1 = cA + (size_t)(t + 1) * kstepA;
;             const char* a2 = last ? nA : cA + (size_t)(t + 2) * kstepA; const char* b2 = last ? nB : cB + (size_t)(t + 2) * kstep;
;             const char* a3 = a2 + kstepA; const char* b3 = b2 + kstep;
;             PG8_LDB(B0, 0, 0); PG8_LDB(B1, 0, 1); PG8_SCHED; PG8_LDA(At, 0, 0); PG8_STAGE(PG8_SA(1, 1), a1 + hstepA, voffA);
.LBB0_900:
	s_ashr_i32 s21, s20, 31
	s_lshl_b64 s[22:23], s[20:21], 20
	s_add_u32 s2, s68, s22
	s_addc_u32 s19, s69, s23
	s_and_b64 s[22:23], s[0:1], exec
	s_cselect_b32 s2, s2, s28
	s_cselect_b32 s19, s19, s29
	s_add_u32 s22, s2, s24
	s_addc_u32 s23, s19, s25
	s_ashr_i32 s19, s18, 31
	s_lshl_b64 s[34:35], s[18:19], 20
	s_add_u32 s2, s78, s34
	s_addc_u32 s19, s79, s35
	s_and_b64 s[34:35], s[0:1], exec
	s_cselect_b32 s2, s2, s30
	s_cselect_b32 s19, s19, s31
	s_add_u32 s24, s2, s24
	s_addc_u32 s25, s19, s25
	s_add_u32 s28, s28, 0x80080
	s_addc_u32 s29, s29, 0
	s_add_u32 s19, s30, 0x100
	s_addc_u32 s21, s31, 0
	s_mov_b32 s49, -2
	s_and_b32 s2, s3, 0xfff
	s_mov_b32 s49, 0
	s_cmp_lt_u32 s3, 0x1000
	s_cbranch_scc0 .Lp8k_B_init
	s_setprio 1
	s_mov_b64 s[50:51], s[24:25]
	s_cmp_eq_u32 s42, 1
	s_cbranch_scc1 .Lp8k_A_first
	s_add_u32 s28, s30, 0x100
	s_addc_u32 s29, s31, 0
	ds_read_b128 v[156:159], v153 offset:0
	ds_read_b128 v[160:163], v153 offset:1024
	s_branch .Lp8k_A_entry

; #define PG8_STAGE(bufoff, gbase, voff) do { _Pragma("unroll") for (int _i = 0; _i < 2; ++_i) \
;         __builtin_amdgcn_global_load_lds((const unsigned*)((const char*)(gbase) + (voff)[_i]), (PG8_LAS unsigned*)(lds + (bufoff) + ldsw + _i * 8192), 16, 0, 0); } while (0)
; #define PG8_LDA(dst, b, h) do { _Pragma("unroll") for (int m = 0; m < 4; ++m) _Pragma("unroll") for (int k = 0; k < 2; ++k) dst[m][k] = *(const PG8_LAS bf16x8*)(lds + PG8_SA(b, h) + aoff + m * 2048 + k * 1024); } while (0)
; #define PG8_LDB(dst, b, h) do { _Pragma("unroll") for (int n = 0; n < 2; ++n) _Pragma("unroll") for (int k = 0; k < 2; ++k) dst[n][k] = *(const PG8_LAS bf16x8*)(lds + PG8_SB(b, h) + boff + n * 2048 + k * 1024); } while (0)
; #define PG8_SCHED __builtin_amdgcn_sched_barrier(0)
; template <class Epi, class Sched, bool ALIGN_EPI>
; __device__ __forceinline__ void gemm_phase(PG8_LAS unsigned char* lds, const Gemm g, const Sched& S, const Epi& E) {
;     ...
;         for (int t = 0; t < nt; t += 2) {
;             if constexpr (Epi::MIDK) { if (t == (nt >> 1)) E.midk(acc, cur, wr, fr); }
;             const bool last = (t == nt - 2);
;             const char* a1 = cA + (size_t)(t + 1) * kstepA;
;             const char* a2 = last ? nA : cA + (size_t)(t + 2) * kstepA; const char* b2 = last ? nB : cB + (size_t)(t + 2) * kstep;
;             const char* a3 = a2 + kstepA; const char* b3 = b2 + kstep;
;             PG8_LDB(B0, 0, 0); PG8_LDB(B1, 0, 1); PG8_SCHED; PG8_LDA(At, 0, 0); PG8_STAGE(PG8_SA(1, 1), a1 + hstepA, voffA);
.Lp8k_B_init:
	s_setprio 0
	s_sub_u32 s28, s28, 0xa0000
	s_subb_u32 s29, s29, 0
	s_sub_u32 s50, s22, 0x20000
	s_subb_u32 s51, s23, 0
	s_cmp_eq_u32 s42, 1
	s_cbranch_scc1 .Lp8k_B_nobar
	s_barrier

;     __host__ __device__ bool next(int i, Unit& u) const { const int L = i * G + c; if (L >= n) return false; u.pm = L; u.pn = L >> 2; return true; }
; #define PG8_STAGE(bufoff, gbase, voff) do { _Pragma("unroll") for (int _i = 0; _i < 2; ++_i) \
;         __builtin_amdgcn_global_load_lds((const unsigned*)((const char*)(gbase) + (voff)[_i]), (PG8_LAS unsigned*)(lds + (bufoff) + ldsw + _i * 8192), 16, 0, 0); } while (0)
; #define PG8_LDA(dst, b, h) do { _Pragma("unroll") for (int m = 0; m < 4; ++m) _Pragma("unroll") for (int k = 0; k < 2; ++k) dst[m][k] = *(const PG8_LAS bf16x8*)(lds + PG8_SA(b, h) + aoff + m * 2048 + k * 1024); } while (0)
; #define PG8_LDB(dst, b, h) do { _Pragma("unroll") for (int n = 0; n < 2; ++n) _Pragma("unroll") for (int k = 0; k < 2; ++k) dst[n][k] = *(const PG8_LAS bf16x8*)(lds + PG8_SB(b, h) + boff + n * 2048 + k * 1024); } while (0)
; #define PG8_WAIT_V(n) asm volatile("s_waitcnt vmcnt(" #n ")" ::: "memory")
; #define PG8_WAIT_L(n) asm volatile("s_waitcnt lgkmcnt(" #n ")" ::: "memory")
; #define PG8_BAR __builtin_amdgcn_s_barrier()
; #define PG8_SCHED __builtin_amdgcn_sched_barrier(0)
; template <class Epi, class Sched, bool ALIGN_EPI>
; __device__ __forceinline__ void gemm_phase(PG8_LAS unsigned char* lds, const Gemm g, const Sched& S, const Epi& E) {
;     ...
;         const bool has_next = S.next(ui + 1, nxt);
;         const size_t tail_ = has_next ? 0 : tailoff; const char* nA = (has_next ? (const char*)g.A + (size_t)nxt.pm * tstepA : cA) + (has_next ? 0 : tailoffA); const char* nB = (has_next ? (const char*)g.Bt + (size_t)nxt.pn * tstepB : cB) + tail_;
;         for (int t = 0; t < nt; t += 2) {
;             if constexpr (Epi::MIDK) { if (t == (nt >> 1)) E.midk(acc, cur, wr, fr); }
;             const bool last = (t == nt - 2);
;             const char* a1 = cA + (size_t)(t + 1) * kstepA;
;             const char* a2 = last ? nA : cA + (size_t)(t + 2) * kstepA; const char* b2 = last ? nB : cB + (size_t)(t + 2) * kstep;
;             const char* a3 = a2 + kstepA; const char* b3 = b2 + kstep;
;             PG8_LDB(B0, 0, 0); PG8_LDB(B1, 0, 1); PG8_SCHED; PG8_LDA(At, 0, 0); PG8_STAGE(PG8_SA(1, 1), a1 + hstepA, voffA);
;             PG8_WAIT_V(8); PG8_WAIT_L(0); PG8_BAR; PG8_MMA(0, 0, At, B0); PG8_MMA(0, 1, At, B1); PG8_BAR; PG8_SCHED;
.LBB0_947:
	s_add_u32 s6, s6, s30
	s_addc_u32 s7, s7, s31
	s_add_u32 s24, s34, s24
	s_addc_u32 s25, s35, s25
	s_add_u32 s57, s28, 0x100
	s_addc_u32 s58, s29, 0
	s_mov_b32 s59, -2
	s_and_b32 s60, s37, 0xfff
	s_mov_b32 s57, 0
	s_cmp_lt_u32 s37, 0x1000
	s_cbranch_scc0 .Lp9k_B_init
	s_setprio 1
	s_add_u32 s28, s28, 0x80
	s_addc_u32 s29, s29, 0
	s_mov_b64 s[58:59], s[24:25]
	ds_read_b128 v[194:197], v157 offset:0
	ds_read_b128 v[198:201], v157 offset:1024
	ds_read_b128 v[202:205], v157 offset:2048
	s_add_i32 m0, s60, 0x18000
	s_nop 0
	global_load_lds_dwordx4 v132, s[28:29]
	ds_read_b128 v[206:209], v157 offset:3072
	ds_read_b128 v[210:213], v157 offset:4096
	ds_read_b128 v[214:217], v157 offset:5120
	s_add_i32 m0, s60, 0x1a000
	s_nop 0
	global_load_lds_dwordx4 v136, s[28:29]
	ds_read_b128 v[218:221], v157 offset:6144
	ds_read_b128 v[222:225], v157 offset:7168
	ds_read_b128 v[158:161], v155 offset:0
	s_add_u32 s30, s28, 0x58000
	s_addc_u32 s31, s29, 0
	s_add_i32 m0, s60, 0x19000
	s_nop 0
	global_load_lds_dwordx4 v132, s[30:31]
	ds_read_b128 v[162:165], v155 offset:1024
	ds_read_b128 v[166:169], v155 offset:2048
	ds_read_b128 v[174:177], v155 offset:3072
	s_add_i32 m0, s60, 0x1b000
	s_nop 0
	global_load_lds_dwordx4 v136, s[30:31]
	ds_read_b128 v[178:181], v155 offset:16384
	ds_read_b128 v[182:185], v155 offset:17408
	ds_read_b128 v[186:189], v155 offset:18432
	s_add_u32 s30, s28, 0x160000
	s_addc_u32 s31, s29, 0
	s_add_i32 m0, s60, 0x1c000
	s_nop 0
	global_load_lds_dwordx4 v132, s[30:31]
	ds_read_b128 v[190:193], v155 offset:19456
	ds_read_b128 v[226:229], v157 offset:16384
	ds_read_b128 v[230:233], v157 offset:17408
	s_add_i32 m0, s60, 0x1e000
	s_nop 0
	global_load_lds_dwordx4 v136, s[30:31]
	ds_read_b128 v[234:237], v157 offset:18432
	ds_read_b128 v[238:241], v157 offset:19456
	ds_read_b128 v[242:245], v157 offset:20480
	s_add_u32 s30, s28, 0x1b8000
	s_addc_u32 s31, s29, 0
	s_add_i32 m0, s60, 0x1d000
	s_nop 0
	global_load_lds_dwordx4 v132, s[30:31]
	ds_read_b128 v[246:249], v157 offset:21504
	ds_read_b128 v[250:253], v157 offset:22528
	ds_read_b128 v[142:145], v157 offset:23552
	s_add_i32 m0, s60, 0x1f000
	s_nop 0
	global_load_lds_dwordx4 v136, s[30:31]
	s_add_u32 s28, s28, 0x80
	s_addc_u32 s29, s29, 0
	s_waitcnt vmcnt(8) lgkmcnt(0)
	s_barrier
	v_mfma_f32_16x16x32_bf16 v[126:129], v[158:161], v[194:197], 0
	v_mfma_f32_16x16x32_bf16 v[126:129], v[162:165], v[198:201], v[126:129]
	v_mfma_f32_16x16x32_bf16 v[122:125], v[174:177], v[198:201], 0
	v_mfma_f32_16x16x32_bf16 v[122:125], v[166:169], v[194:197], v[122:125]
	v_mfma_f32_16x16x32_bf16 v[114:117], v[178:181], v[194:197], 0
	v_mfma_f32_16x16x32_bf16 v[114:117], v[182:185], v[198:201], v[114:117]
	v_mfma_f32_16x16x32_bf16 v[106:109], v[190:193], v[198:201], 0
	v_mfma_f32_16x16x32_bf16 v[106:109], v[186:189], v[194:197], v[106:109]
	v_mfma_f32_16x16x32_bf16 v[90:93], v[186:189], v[202:205], 0
	v_mfma_f32_16x16x32_bf16 v[90:93], v[190:193], v[206:209], v[90:93]
	v_mfma_f32_16x16x32_bf16 v[98:101], v[182:185], v[206:209], 0
	v_mfma_f32_16x16x32_bf16 v[98:101], v[178:181], v[202:205], v[98:101]
	v_mfma_f32_16x16x32_bf16 v[110:113], v[166:169], v[202:205], 0
	v_mfma_f32_16x16x32_bf16 v[110:113], v[174:177], v[206:209], v[110:113]
	v_mfma_f32_16x16x32_bf16 v[118:121], v[162:165], v[206:209], 0
	v_mfma_f32_16x16x32_bf16 v[118:121], v[158:161], v[202:205], v[118:121]
	v_mfma_f32_16x16x32_bf16 v[102:105], v[158:161], v[210:213], 0
	v_mfma_f32_16x16x32_bf16 v[102:105], v[162:165], v[214:217], v[102:105]
	v_mfma_f32_16x16x32_bf16 v[94:97], v[174:177], v[214:217], 0
	v_mfma_f32_16x16x32_bf16 v[94:97], v[166:169], v[210:213], v[94:97]
	v_mfma_f32_16x16x32_bf16 v[82:85], v[178:181], v[210:213], 0
	v_mfma_f32_16x16x32_bf16 v[82:85], v[182:185], v[214:217], v[82:85]
	v_mfma_f32_16x16x32_bf16 v[74:77], v[190:193], v[214:217], 0
	v_mfma_f32_16x16x32_bf16 v[74:77], v[186:189], v[210:213], v[74:77]
	v_mfma_f32_16x16x32_bf16 v[66:69], v[186:189], v[218:221], 0
	v_mfma_f32_16x16x32_bf16 v[66:69], v[190:193], v[222:225], v[66:69]
	v_mfma_f32_16x16x32_bf16 v[70:73], v[182:185], v[222:225], 0
	v_mfma_f32_16x16x32_bf16 v[70:73], v[178:181], v[218:221], v[70:73]
	v_mfma_f32_16x16x32_bf16 v[78:81], v[166:169], v[218:221], 0
	v_mfma_f32_16x16x32_bf16 v[78:81], v[174:177], v[222:225], v[78:81]
	v_mfma_f32_16x16x32_bf16 v[86:89], v[162:165], v[222:225], 0
	v_mfma_f32_16x16x32_bf16 v[86:89], v[158:161], v[218:221], v[86:89]
	v_mfma_f32_16x16x32_bf16 v[62:65], v[158:161], v[226:229], 0
	v_mfma_f32_16x16x32_bf16 v[62:65], v[162:165], v[230:233], v[62:65]
	v_mfma_f32_16x16x32_bf16 v[58:61], v[174:177], v[230:233], 0
	v_mfma_f32_16x16x32_bf16 v[58:61], v[166:169], v[226:229], v[58:61]
	v_mfma_f32_16x16x32_bf16 v[50:53], v[178:181], v[226:229], 0
	v_mfma_f32_16x16x32_bf16 v[50:53], v[182:185], v[230:233], v[50:53]
	v_mfma_f32_16x16x32_bf16 v[42:45], v[190:193], v[230:233], 0
	v_mfma_f32_16x16x32_bf16 v[42:45], v[186:189], v[226:229], v[42:45]
	v_mfma_f32_16x16x32_bf16 v[26:29], v[186:189], v[234:237], 0
	v_mfma_f32_16x16x32_bf16 v[26:29], v[190:193], v[238:241], v[26:29]
	v_mfma_f32_16x16x32_bf16 v[34:37], v[182:185], v[238:241], 0
	v_mfma_f32_16x16x32_bf16 v[34:37], v[178:181], v[234:237], v[34:37]
	v_mfma_f32_16x16x32_bf16 v[46:49], v[166:169], v[234:237], 0
	v_mfma_f32_16x16x32_bf16 v[46:49], v[174:177], v[238:241], v[46:49]
	v_mfma_f32_16x16x32_bf16 v[54:57], v[162:165], v[238:241], 0
	v_mfma_f32_16x16x32_bf16 v[54:57], v[158:161], v[234:237], v[54:57]
	v_mfma_f32_16x16x32_bf16 v[38:41], v[158:161], v[242:245], 0
	v_mfma_f32_16x16x32_bf16 v[38:41], v[162:165], v[246:249], v[38:41]
	v_mfma_f32_16x16x32_bf16 v[30:33], v[174:177], v[246:249], 0
	v_mfma_f32_16x16x32_bf16 v[30:33], v[166:169], v[242:245], v[30:33]
	v_mfma_f32_16x16x32_bf16 v[18:21], v[178:181], v[242:245], 0
	v_mfma_f32_16x16x32_bf16 v[18:21], v[182:185], v[246:249], v[18:21]
	v_mfma_f32_16x16x32_bf16 v[10:13], v[190:193], v[246:249], 0
	v_mfma_f32_16x16x32_bf16 v[10:13], v[186:189], v[242:245], v[10:13]
	v_mfma_f32_16x16x32_bf16 v[2:5], v[186:189], v[250:253], 0
	v_mfma_f32_16x16x32_bf16 v[2:5], v[190:193], v[142:145], v[2:5]
	v_mfma_f32_16x16x32_bf16 v[6:9], v[182:185], v[142:145], 0
	v_mfma_f32_16x16x32_bf16 v[6:9], v[178:181], v[250:253], v[6:9]
	v_mfma_f32_16x16x32_bf16 v[14:17], v[166:169], v[250:253], 0
	v_mfma_f32_16x16x32_bf16 v[14:17], v[174:177], v[142:145], v[14:17]
	v_mfma_f32_16x16x32_bf16 v[22:25], v[162:165], v[142:145], 0
	v_mfma_f32_16x16x32_bf16 v[22:25], v[158:161], v[250:253], v[22:25]
	s_waitcnt vmcnt(0)
	s_barrier
; #define PG8_STAGE(bufoff, gbase, voff) do { _Pragma("unroll") for (int _i = 0; _i < 2; ++_i) \
;         __builtin_amdgcn_global_load_lds((const unsigned*)((const char*)(gbase) + (voff)[_i]), (PG8_LAS unsigned*)(lds + (bufoff) + ldsw + _i * 8192), 16, 0, 0); } while (0)
; #define PG8_LDA(dst, b, h) do { _Pragma("unroll") for (int m = 0; m < 4; ++m) _Pragma("unroll") for (int k = 0; k < 2; ++k) dst[m][k] = *(const PG8_LAS bf16x8*)(lds + PG8_SA(b, h) + aoff + m * 2048 + k * 1024); } while (0)
; #define PG8_LDB(dst, b, h) do { _Pragma("unroll") for (int n = 0; n < 2; ++n) _Pragma("unroll") for (int k = 0; k < 2; ++k) dst[n][k] = *(const PG8_LAS bf16x8*)(lds + PG8_SB(b, h) + boff + n * 2048 + k * 1024); } while (0)
; template <class Epi, class Sched, bool ALIGN_EPI>
; __device__ __forceinline__ void gemm_phase(PG8_LAS unsigned char* lds, const Gemm g, const Sched& S, const Epi& E) {
;     ...
;         for (int t = 0; t < nt; t += 2) {
;             if constexpr (Epi::MIDK) { if (t == (nt >> 1)) E.midk(acc, cur, wr, fr); }
;             const bool last = (t == nt - 2);
;             const char* a1 = cA + (size_t)(t + 1) * kstepA;
;             const char* a2 = last ? nA : cA + (size_t)(t + 2) * kstepA; const char* b2 = last ? nB : cB + (size_t)(t + 2) * kstep;
;             const char* a3 = a2 + kstepA; const char* b3 = b2 + kstep;
;             PG8_LDB(B0, 0, 0); PG8_LDB(B1, 0, 1); PG8_SCHED; PG8_LDA(At, 0, 0); PG8_STAGE(PG8_SA(1, 1), a1 + hstepA, voffA);
;             PG8_WAIT_V(8); PG8_WAIT_L(0); PG8_BAR; PG8_MMA(0, 0, At, B0); PG8_MMA(0, 1, At, B1); PG8_BAR; PG8_SCHED;
;             PG8_LDA(At, 0, 1); PG8_STAGE(PG8_SB(0, 0), b2, voffB); PG8_STAGE(PG8_SB(0, 1), b2 + hstepB, voffB); PG8_STAGE(PG8_SA(0, 0), a2, voffA);
;             PG8_WAIT_V(8); PG8_WAIT_L(0); PG8_BAR; PG8_MMA(1, 0, At, B0); PG8_MMA(1, 1, At, B1); PG8_BAR; PG8_SCHED;
;             PG8_LDB(B0, 1, 0); PG8_LDB(B1, 1, 1); PG8_SCHED; PG8_LDA(At, 1, 0); PG8_STAGE(PG8_SA(0, 1), a2 + hstepA, voffA);
;             PG8_WAIT_V(8); PG8_WAIT_L(0); PG8_BAR; PG8_MMA(0, 0, At, B0); PG8_MMA(0, 1, At, B1); PG8_BAR; PG8_SCHED;
;             PG8_LDA(At, 1, 1); PG8_STAGE(PG8_SB(1, 0), b3, voffB); PG8_STAGE(PG8_SB(1, 1), b3 + hstepB, voffB); PG8_STAGE(PG8_SA(1, 0), a3, voffA);
;             PG8_WAIT_V(8); PG8_WAIT_L(0); PG8_BAR; PG8_MMA(1, 0, At, B0); PG8_MMA(1, 1, At, B1); PG8_BAR; PG8_SCHED;
;         }
	ds_read_b128 v[194:197], v157 offset:32768
	ds_read_b128 v[198:201], v157 offset:33792
	ds_read_b128 v[202:205], v157 offset:34816
	s_cmp_eq_u32 s57, 43
	s_cselect_b32 s28, s58, s28
	s_cselect_b32 s29, s59, s29
	s_add_i32 m0, s60, 0x10000
	s_nop 0
	global_load_lds_dwordx4 v132, s[28:29]
	ds_read_b128 v[206:209], v157 offset:35840
	ds_read_b128 v[210:213], v157 offset:36864
	ds_read_b128 v[214:217], v157 offset:37888
	s_add_i32 m0, s60, 0x12000
	s_nop 0
	global_load_lds_dwordx4 v136, s[28:29]
	ds_read_b128 v[218:221], v157 offset:38912
	ds_read_b128 v[222:225], v157 offset:39936
	ds_read_b128 v[158:161], v155 offset:32768
	s_add_u32 s30, s28, 0x58000
	s_addc_u32 s31, s29, 0
	s_add_i32 m0, s60, 0x11000
	s_nop 0
	global_load_lds_dwordx4 v132, s[30:31]
	ds_read_b128 v[162:165], v155 offset:33792
	ds_read_b128 v[166:169], v155 offset:34816
	ds_read_b128 v[174:177], v155 offset:35840
	s_add_i32 m0, s60, 0x13000
	s_nop 0
	global_load_lds_dwordx4 v136, s[30:31]
	ds_read_b128 v[178:181], v155 offset:49152
	ds_read_b128 v[182:185], v155 offset:50176
	ds_read_b128 v[186:189], v155 offset:51200
	s_add_u32 s30, s28, 0x160000
	s_addc_u32 s31, s29, 0
	s_add_i32 m0, s60, 0x14000
	s_nop 0
	global_load_lds_dwordx4 v132, s[30:31]
	ds_read_b128 v[190:193], v155 offset:52224
	ds_read_b128 v[226:229], v157 offset:49152
	ds_read_b128 v[230:233], v157 offset:50176
	s_add_i32 m0, s60, 0x16000
	s_nop 0
	global_load_lds_dwordx4 v136, s[30:31]
	ds_read_b128 v[234:237], v157 offset:51200
	ds_read_b128 v[238:241], v157 offset:52224
	ds_read_b128 v[242:245], v157 offset:53248
	s_add_u32 s30, s28, 0x1b8000
	s_addc_u32 s31, s29, 0
	s_add_i32 m0, s60, 0x15000
	s_nop 0
	global_load_lds_dwordx4 v132, s[30:31]
	ds_read_b128 v[246:249], v157 offset:54272
	ds_read_b128 v[250:253], v157 offset:55296
	ds_read_b128 v[142:145], v157 offset:56320
	s_add_i32 m0, s60, 0x17000
	s_nop 0
	global_load_lds_dwordx4 v136, s[30:31]
	s_add_u32 s28, s28, 0x80
	s_addc_u32 s29, s29, 0
	s_waitcnt vmcnt(8) lgkmcnt(0)
	s_barrier
	v_mfma_f32_16x16x32_bf16 v[126:129], v[158:161], v[194:197], v[126:129]
	v_mfma_f32_16x16x32_bf16 v[126:129], v[162:165], v[198:201], v[126:129]
	v_mfma_f32_16x16x32_bf16 v[122:125], v[174:177], v[198:201], v[122:125]
	v_mfma_f32_16x16x32_bf16 v[122:125], v[166:169], v[194:197], v[122:125]
	v_mfma_f32_16x16x32_bf16 v[114:117], v[178:181], v[194:197], v[114:117]
	v_mfma_f32_16x16x32_bf16 v[114:117], v[182:185], v[198:201], v[114:117]
	v_mfma_f32_16x16x32_bf16 v[106:109], v[190:193], v[198:201], v[106:109]
	v_mfma_f32_16x16x32_bf16 v[106:109], v[186:189], v[194:197], v[106:109]
	v_mfma_f32_16x16x32_bf16 v[90:93], v[186:189], v[202:205], v[90:93]
	v_mfma_f32_16x16x32_bf16 v[90:93], v[190:193], v[206:209], v[90:93]
	v_mfma_f32_16x16x32_bf16 v[98:101], v[182:185], v[206:209], v[98:101]
	v_mfma_f32_16x16x32_bf16 v[98:101], v[178:181], v[202:205], v[98:101]
	v_mfma_f32_16x16x32_bf16 v[110:113], v[166:169], v[202:205], v[110:113]
	v_mfma_f32_16x16x32_bf16 v[110:113], v[174:177], v[206:209], v[110:113]
	v_mfma_f32_16x16x32_bf16 v[118:121], v[162:165], v[206:209], v[118:121]
	v_mfma_f32_16x16x32_bf16 v[118:121], v[158:161], v[202:205], v[118:121]
	v_mfma_f32_16x16x32_bf16 v[102:105], v[158:161], v[210:213], v[102:105]
	v_mfma_f32_16x16x32_bf16 v[102:105], v[162:165], v[214:217], v[102:105]
	v_mfma_f32_16x16x32_bf16 v[94:97], v[174:177], v[214:217], v[94:97]
	v_mfma_f32_16x16x32_bf16 v[94:97], v[166:169], v[210:213], v[94:97]
	v_mfma_f32_16x16x32_bf16 v[82:85], v[178:181], v[210:213], v[82:85]
	v_mfma_f32_16x16x32_bf16 v[82:85], v[182:185], v[214:217], v[82:85]
	v_mfma_f32_16x16x32_bf16 v[74:77], v[190:193], v[214:217], v[74:77]
	v_mfma_f32_16x16x32_bf16 v[74:77], v[186:189], v[210:213], v[74:77]
	v_mfma_f32_16x16x32_bf16 v[66:69], v[186:189], v[218:221], v[66:69]
	v_mfma_f32_16x16x32_bf16 v[66:69], v[190:193], v[222:225], v[66:69]
	v_mfma_f32_16x16x32_bf16 v[70:73], v[182:185], v[222:225], v[70:73]
	v_mfma_f32_16x16x32_bf16 v[70:73], v[178:181], v[218:221], v[70:73]
	v_mfma_f32_16x16x32_bf16 v[78:81], v[166:169], v[218:221], v[78:81]
	v_mfma_f32_16x16x32_bf16 v[78:81], v[174:177], v[222:225], v[78:81]
	v_mfma_f32_16x16x32_bf16 v[86:89], v[162:165], v[222:225], v[86:89]
	v_mfma_f32_16x16x32_bf16 v[86:89], v[158:161], v[218:221], v[86:89]
	v_mfma_f32_16x16x32_bf16 v[62:65], v[158:161], v[226:229], v[62:65]
	v_mfma_f32_16x16x32_bf16 v[62:65], v[162:165], v[230:233], v[62:65]
	v_mfma_f32_16x16x32_bf16 v[58:61], v[174:177], v[230:233], v[58:61]
	v_mfma_f32_16x16x32_bf16 v[58:61], v[166:169], v[226:229], v[58:61]
	v_mfma_f32_16x16x32_bf16 v[50:53], v[178:181], v[226:229], v[50:53]
	v_mfma_f32_16x16x32_bf16 v[50:53], v[182:185], v[230:233], v[50:53]
	v_mfma_f32_16x16x32_bf16 v[42:45], v[190:193], v[230:233], v[42:45]
	v_mfma_f32_16x16x32_bf16 v[42:45], v[186:189], v[226:229], v[42:45]
	v_mfma_f32_16x16x32_bf16 v[26:29], v[186:189], v[234:237], v[26:29]
	v_mfma_f32_16x16x32_bf16 v[26:29], v[190:193], v[238:241], v[26:29]
	v_mfma_f32_16x16x32_bf16 v[34:37], v[182:185], v[238:241], v[34:37]
	v_mfma_f32_16x16x32_bf16 v[34:37], v[178:181], v[234:237], v[34:37]
	v_mfma_f32_16x16x32_bf16 v[46:49], v[166:169], v[234:237], v[46:49]
	v_mfma_f32_16x16x32_bf16 v[46:49], v[174:177], v[238:241], v[46:49]
	v_mfma_f32_16x16x32_bf16 v[54:57], v[162:165], v[238:241], v[54:57]
	v_mfma_f32_16x16x32_bf16 v[54:57], v[158:161], v[234:237], v[54:57]
	v_mfma_f32_16x16x32_bf16 v[38:41], v[158:161], v[242:245], v[38:41]
	v_mfma_f32_16x16x32_bf16 v[38:41], v[162:165], v[246:249], v[38:41]
	v_mfma_f32_16x16x32_bf16 v[30:33], v[174:177], v[246:249], v[30:33]
	v_mfma_f32_16x16x32_bf16 v[30:33], v[166:169], v[242:245], v[30:33]
	v_mfma_f32_16x16x32_bf16 v[18:21], v[178:181], v[242:245], v[18:21]
	v_mfma_f32_16x16x32_bf16 v[18:21], v[182:185], v[246:249], v[18:21]
	v_mfma_f32_16x16x32_bf16 v[10:13], v[190:193], v[246:249], v[10:13]
	v_mfma_f32_16x16x32_bf16 v[10:13], v[186:189], v[242:245], v[10:13]
	v_mfma_f32_16x16x32_bf16 v[2:5], v[186:189], v[250:253], v[2:5]
	v_mfma_f32_16x16x32_bf16 v[2:5], v[190:193], v[142:145], v[2:5]
	v_mfma_f32_16x16x32_bf16 v[6:9], v[182:185], v[142:145], v[6:9]
	v_mfma_f32_16x16x32_bf16 v[6:9], v[178:181], v[250:253], v[6:9]
	v_mfma_f32_16x16x32_bf16 v[14:17], v[166:169], v[250:253], v[14:17]
	v_mfma_f32_16x16x32_bf16 v[14:17], v[174:177], v[142:145], v[14:17]
	v_mfma_f32_16x16x32_bf16 v[22:25], v[162:165], v[142:145], v[22:25]
	v_mfma_f32_16x16x32_bf16 v[22:25], v[158:161], v[250:253], v[22:25]
	s_waitcnt vmcnt(0)
	s_barrier
	s_add_i32 s57, s57, 1

; #define PG8_STAGE(bufoff, gbase, voff) do { _Pragma("unroll") for (int _i = 0; _i < 2; ++_i) \
;         __builtin_amdgcn_global_load_lds((const unsigned*)((const char*)(gbase) + (voff)[_i]), (PG8_LAS unsigned*)(lds + (bufoff) + ldsw + _i * 8192), 16, 0, 0); } while (0)
; #define PG8_LDA(dst, b, h) do { _Pragma("unroll") for (int m = 0; m < 4; ++m) _Pragma("unroll") for (int k = 0; k < 2; ++k) dst[m][k] = *(const PG8_LAS bf16x8*)(lds + PG8_SA(b, h) + aoff + m * 2048 + k * 1024); } while (0)
; #define PG8_LDB(dst, b, h) do { _Pragma("unroll") for (int n = 0; n < 2; ++n) _Pragma("unroll") for (int k = 0; k < 2; ++k) dst[n][k] = *(const PG8_LAS bf16x8*)(lds + PG8_SB(b, h) + boff + n * 2048 + k * 1024); } while (0)
; template <class Epi, class Sched, bool ALIGN_EPI>
; __device__ __forceinline__ void gemm_phase(PG8_LAS unsigned char* lds, const Gemm g, const Sched& S, const Epi& E) {
;     ...
;         for (int t = 0; t < nt; t += 2) {
;             if constexpr (Epi::MIDK) { if (t == (nt >> 1)) E.midk(acc, cur, wr, fr); }
;             const bool last = (t == nt - 2);
;             const char* a1 = cA + (size_t)(t + 1) * kstepA;
;             const char* a2 = last ? nA : cA + (size_t)(t + 2) * kstepA; const char* b2 = last ? nB : cB + (size_t)(t + 2) * kstep;
;             const char* a3 = a2 + kstepA; const char* b3 = b2 + kstep;
;             PG8_LDB(B0, 0, 0); PG8_LDB(B1, 0, 1); PG8_SCHED; PG8_LDA(At, 0, 0); PG8_STAGE(PG8_SA(1, 1), a1 + hstepA, voffA);
;             PG8_WAIT_V(8); PG8_WAIT_L(0); PG8_BAR; PG8_MMA(0, 0, At, B0); PG8_MMA(0, 1, At, B1); PG8_BAR; PG8_SCHED;
;             PG8_LDA(At, 0, 1); PG8_STAGE(PG8_SB(0, 0), b2, voffB); PG8_STAGE(PG8_SB(0, 1), b2 + hstepB, voffB); PG8_STAGE(PG8_SA(0, 0), a2, voffA);
;             PG8_WAIT_V(8); PG8_WAIT_L(0); PG8_BAR; PG8_MMA(1, 0, At, B0); PG8_MMA(1, 1, At, B1); PG8_BAR; PG8_SCHED;
;             PG8_LDB(B0, 1, 0); PG8_LDB(B1, 1, 1); PG8_SCHED; PG8_LDA(At, 1, 0); PG8_STAGE(PG8_SA(0, 1), a2 + hstepA, voffA);
;             PG8_WAIT_V(8); PG8_WAIT_L(0); PG8_BAR; PG8_MMA(0, 0, At, B0); PG8_MMA(0, 1, At, B1); PG8_BAR; PG8_SCHED;
;             PG8_LDA(At, 1, 1); PG8_STAGE(PG8_SB(1, 0), b3, voffB); PG8_STAGE(PG8_SB(1, 1), b3 + hstepB, voffB); PG8_STAGE(PG8_SA(1, 0), a3, voffA);
;             PG8_WAIT_V(8); PG8_WAIT_L(0); PG8_BAR; PG8_MMA(1, 0, At, B0); PG8_MMA(1, 1, At, B1); PG8_BAR; PG8_SCHED;
;         }
.Lp9k_B_init:
	s_setprio 0
	s_sub_u32 s28, s26, 0x57f80
	s_subb_u32 s29, s27, 0
	s_sub_u32 s58, s6, 0x58000
	s_subb_u32 s59, s7, 0
	ds_read_b128 v[194:197], v157 offset:0
	ds_read_b128 v[198:201], v157 offset:1024
	ds_read_b128 v[202:205], v157 offset:2048
	s_add_i32 m0, s60, 0xa000
	s_nop 0
	global_load_lds_dwordx4 v134, s[28:29]
	ds_read_b128 v[206:209], v157 offset:3072
	ds_read_b128 v[210:213], v157 offset:4096
	ds_read_b128 v[214:217], v157 offset:5120
	s_add_u32 s30, s28, 0x58000
	s_addc_u32 s31, s29, 0
	s_add_i32 m0, s60, 0xb000
	s_nop 0
	global_load_lds_dwordx4 v134, s[30:31]
	ds_read_b128 v[218:221], v157 offset:6144
	ds_read_b128 v[222:225], v157 offset:7168
	ds_read_b128 v[158:161], v155 offset:0
	s_add_u32 s30, s28, 0x160000
	s_addc_u32 s31, s29, 0
	s_add_i32 m0, s60, 0xe000
	s_nop 0
	global_load_lds_dwordx4 v134, s[30:31]
	ds_read_b128 v[162:165], v155 offset:1024
	ds_read_b128 v[166:169], v155 offset:2048
	ds_read_b128 v[174:177], v155 offset:3072
	s_add_u32 s30, s28, 0x1b8000
	s_addc_u32 s31, s29, 0
	s_add_i32 m0, s60, 0xf000
	s_nop 0
	global_load_lds_dwordx4 v134, s[30:31]
	ds_read_b128 v[178:181], v155 offset:16384
	ds_read_b128 v[182:185], v155 offset:17408
	ds_read_b128 v[186:189], v155 offset:18432
	s_add_u32 s34, s28, 0x80
	s_addc_u32 s35, s29, 0
	s_cmp_eq_u32 s57, 43
	s_cselect_b32 s34, s58, s34
	s_cselect_b32 s35, s59, s35
	s_add_i32 m0, s60, 0x0
	s_nop 0
	global_load_lds_dwordx4 v130, s[34:35]
	ds_read_b128 v[190:193], v155 offset:19456
	ds_read_b128 v[226:229], v157 offset:16384
	ds_read_b128 v[230:233], v157 offset:17408
	s_add_u32 s30, s34, 0x58000
	s_addc_u32 s31, s35, 0
	s_add_i32 m0, s60, 0x1000
	s_nop 0
	global_load_lds_dwordx4 v130, s[30:31]
	ds_read_b128 v[234:237], v157 offset:18432
	ds_read_b128 v[238:241], v157 offset:19456
	ds_read_b128 v[242:245], v157 offset:20480
	s_add_u32 s30, s34, 0x160000
	s_addc_u32 s31, s35, 0
	s_add_i32 m0, s60, 0x4000
	s_nop 0
	global_load_lds_dwordx4 v130, s[30:31]
	ds_read_b128 v[246:249], v157 offset:21504
	ds_read_b128 v[250:253], v157 offset:22528
	ds_read_b128 v[142:145], v157 offset:23552
	s_add_u32 s30, s34, 0x1b8000
	s_addc_u32 s31, s35, 0
	s_add_i32 m0, s60, 0x5000
	s_nop 0
	global_load_lds_dwordx4 v130, s[30:31]
	s_add_u32 s28, s28, 0x80
	s_addc_u32 s29, s29, 0
	s_waitcnt vmcnt(8) lgkmcnt(0)
	s_barrier
	v_mfma_f32_16x16x32_bf16 v[126:129], v[158:161], v[194:197], 0
	v_mfma_f32_16x16x32_bf16 v[126:129], v[162:165], v[198:201], v[126:129]
	v_mfma_f32_16x16x32_bf16 v[122:125], v[174:177], v[198:201], 0
	v_mfma_f32_16x16x32_bf16 v[122:125], v[166:169], v[194:197], v[122:125]
	v_mfma_f32_16x16x32_bf16 v[114:117], v[178:181], v[194:197], 0
	v_mfma_f32_16x16x32_bf16 v[114:117], v[182:185], v[198:201], v[114:117]
	v_mfma_f32_16x16x32_bf16 v[106:109], v[190:193], v[198:201], 0
	v_mfma_f32_16x16x32_bf16 v[106:109], v[186:189], v[194:197], v[106:109]
	v_mfma_f32_16x16x32_bf16 v[90:93], v[186:189], v[202:205], 0
	v_mfma_f32_16x16x32_bf16 v[90:93], v[190:193], v[206:209], v[90:93]
	v_mfma_f32_16x16x32_bf16 v[98:101], v[182:185], v[206:209], 0
	v_mfma_f32_16x16x32_bf16 v[98:101], v[178:181], v[202:205], v[98:101]
	v_mfma_f32_16x16x32_bf16 v[110:113], v[166:169], v[202:205], 0
	v_mfma_f32_16x16x32_bf16 v[110:113], v[174:177], v[206:209], v[110:113]
	v_mfma_f32_16x16x32_bf16 v[118:121], v[162:165], v[206:209], 0
	v_mfma_f32_16x16x32_bf16 v[118:121], v[158:161], v[202:205], v[118:121]
	v_mfma_f32_16x16x32_bf16 v[102:105], v[158:161], v[210:213], 0
	v_mfma_f32_16x16x32_bf16 v[102:105], v[162:165], v[214:217], v[102:105]
	v_mfma_f32_16x16x32_bf16 v[94:97], v[174:177], v[214:217], 0
	v_mfma_f32_16x16x32_bf16 v[94:97], v[166:169], v[210:213], v[94:97]
	v_mfma_f32_16x16x32_bf16 v[82:85], v[178:181], v[210:213], 0
	v_mfma_f32_16x16x32_bf16 v[82:85], v[182:185], v[214:217], v[82:85]
	v_mfma_f32_16x16x32_bf16 v[74:77], v[190:193], v[214:217], 0
	v_mfma_f32_16x16x32_bf16 v[74:77], v[186:189], v[210:213], v[74:77]
	v_mfma_f32_16x16x32_bf16 v[66:69], v[186:189], v[218:221], 0
	v_mfma_f32_16x16x32_bf16 v[66:69], v[190:193], v[222:225], v[66:69]
	v_mfma_f32_16x16x32_bf16 v[70:73], v[182:185], v[222:225], 0
	v_mfma_f32_16x16x32_bf16 v[70:73], v[178:181], v[218:221], v[70:73]
	v_mfma_f32_16x16x32_bf16 v[78:81], v[166:169], v[218:221], 0
	v_mfma_f32_16x16x32_bf16 v[78:81], v[174:177], v[222:225], v[78:81]
	v_mfma_f32_16x16x32_bf16 v[86:89], v[162:165], v[222:225], 0
	v_mfma_f32_16x16x32_bf16 v[86:89], v[158:161], v[218:221], v[86:89]
	v_mfma_f32_16x16x32_bf16 v[62:65], v[158:161], v[226:229], 0
	v_mfma_f32_16x16x32_bf16 v[62:65], v[162:165], v[230:233], v[62:65]
	v_mfma_f32_16x16x32_bf16 v[58:61], v[174:177], v[230:233], 0
	v_mfma_f32_16x16x32_bf16 v[58:61], v[166:169], v[226:229], v[58:61]
	v_mfma_f32_16x16x32_bf16 v[50:53], v[178:181], v[226:229], 0
	v_mfma_f32_16x16x32_bf16 v[50:53], v[182:185], v[230:233], v[50:53]
	v_mfma_f32_16x16x32_bf16 v[42:45], v[190:193], v[230:233], 0
	v_mfma_f32_16x16x32_bf16 v[42:45], v[186:189], v[226:229], v[42:45]
	v_mfma_f32_16x16x32_bf16 v[26:29], v[186:189], v[234:237], 0
	v_mfma_f32_16x16x32_bf16 v[26:29], v[190:193], v[238:241], v[26:29]
	v_mfma_f32_16x16x32_bf16 v[34:37], v[182:185], v[238:241], 0
	v_mfma_f32_16x16x32_bf16 v[34:37], v[178:181], v[234:237], v[34:37]
	v_mfma_f32_16x16x32_bf16 v[46:49], v[166:169], v[234:237], 0
	v_mfma_f32_16x16x32_bf16 v[46:49], v[174:177], v[238:241], v[46:49]
	v_mfma_f32_16x16x32_bf16 v[54:57], v[162:165], v[238:241], 0
	v_mfma_f32_16x16x32_bf16 v[54:57], v[158:161], v[234:237], v[54:57]
	v_mfma_f32_16x16x32_bf16 v[38:41], v[158:161], v[242:245], 0
	v_mfma_f32_16x16x32_bf16 v[38:41], v[162:165], v[246:249], v[38:41]
	v_mfma_f32_16x16x32_bf16 v[30:33], v[174:177], v[246:249], 0
	v_mfma_f32_16x16x32_bf16 v[30:33], v[166:169], v[242:245], v[30:33]
	v_mfma_f32_16x16x32_bf16 v[18:21], v[178:181], v[242:245], 0
	v_mfma_f32_16x16x32_bf16 v[18:21], v[182:185], v[246:249], v[18:21]
	v_mfma_f32_16x16x32_bf16 v[10:13], v[190:193], v[246:249], 0
	v_mfma_f32_16x16x32_bf16 v[10:13], v[186:189], v[242:245], v[10:13]
	v_mfma_f32_16x16x32_bf16 v[2:5], v[186:189], v[250:253], 0
	v_mfma_f32_16x16x32_bf16 v[2:5], v[190:193], v[142:145], v[2:5]
	v_mfma_f32_16x16x32_bf16 v[6:9], v[182:185], v[142:145], 0
	v_mfma_f32_16x16x32_bf16 v[6:9], v[178:181], v[250:253], v[6:9]
	v_mfma_f32_16x16x32_bf16 v[14:17], v[166:169], v[250:253], 0
	v_mfma_f32_16x16x32_bf16 v[14:17], v[174:177], v[142:145], v[14:17]
	v_mfma_f32_16x16x32_bf16 v[22:25], v[162:165], v[142:145], 0
	v_mfma_f32_16x16x32_bf16 v[22:25], v[158:161], v[250:253], v[22:25]
	s_waitcnt vmcnt(0)
	s_barrier
; #define PG8_STAGE(bufoff, gbase, voff) do { _Pragma("unroll") for (int _i = 0; _i < 2; ++_i) \
;         __builtin_amdgcn_global_load_lds((const unsigned*)((const char*)(gbase) + (voff)[_i]), (PG8_LAS unsigned*)(lds + (bufoff) + ldsw + _i * 8192), 16, 0, 0); } while (0)
; #define PG8_LDA(dst, b, h) do { _Pragma("unroll") for (int m = 0; m < 4; ++m) _Pragma("unroll") for (int k = 0; k < 2; ++k) dst[m][k] = *(const PG8_LAS bf16x8*)(lds + PG8_SA(b, h) + aoff + m * 2048 + k * 1024); } while (0)
; #define PG8_LDB(dst, b, h) do { _Pragma("unroll") for (int n = 0; n < 2; ++n) _Pragma("unroll") for (int k = 0; k < 2; ++k) dst[n][k] = *(const PG8_LAS bf16x8*)(lds + PG8_SB(b, h) + boff + n * 2048 + k * 1024); } while (0)
; template <class Epi, class Sched, bool ALIGN_EPI>
; __device__ __forceinline__ void gemm_phase(PG8_LAS unsigned char* lds, const Gemm g, const Sched& S, const Epi& E) {
;     ...
;         for (int t = 0; t < nt; t += 2) {
;             if constexpr (Epi::MIDK) { if (t == (nt >> 1)) E.midk(acc, cur, wr, fr); }
;             const bool last = (t == nt - 2);
;             const char* a1 = cA + (size_t)(t + 1) * kstepA;
;             const char* a2 = last ? nA : cA + (size_t)(t + 2) * kstepA; const char* b2 = last ? nB : cB + (size_t)(t + 2) * kstep;
;             const char* a3 = a2 + kstepA; const char* b3 = b2 + kstep;
;             PG8_LDB(B0, 0, 0); PG8_LDB(B1, 0, 1); PG8_SCHED; PG8_LDA(At, 0, 0); PG8_STAGE(PG8_SA(1, 1), a1 + hstepA, voffA);
;             PG8_WAIT_V(8); PG8_WAIT_L(0); PG8_BAR; PG8_MMA(0, 0, At, B0); PG8_MMA(0, 1, At, B1); PG8_BAR; PG8_SCHED;
;             PG8_LDA(At, 0, 1); PG8_STAGE(PG8_SB(0, 0), b2, voffB); PG8_STAGE(PG8_SB(0, 1), b2 + hstepB, voffB); PG8_STAGE(PG8_SA(0, 0), a2, voffA);
;             PG8_WAIT_V(8); PG8_WAIT_L(0); PG8_BAR; PG8_MMA(1, 0, At, B0); PG8_MMA(1, 1, At, B1); PG8_BAR; PG8_SCHED;
;             PG8_LDB(B0, 1, 0); PG8_LDB(B1, 1, 1); PG8_SCHED; PG8_LDA(At, 1, 0); PG8_STAGE(PG8_SA(0, 1), a2 + hstepA, voffA);
;             PG8_WAIT_V(8); PG8_WAIT_L(0); PG8_BAR; PG8_MMA(0, 0, At, B0); PG8_MMA(0, 1, At, B1); PG8_BAR; PG8_SCHED;
;             PG8_LDA(At, 1, 1); PG8_STAGE(PG8_SB(1, 0), b3, voffB); PG8_STAGE(PG8_SB(1, 1), b3 + hstepB, voffB); PG8_STAGE(PG8_SA(1, 0), a3, voffA);
;             PG8_WAIT_V(8); PG8_WAIT_L(0); PG8_BAR; PG8_MMA(1, 0, At, B0); PG8_MMA(1, 1, At, B1); PG8_BAR; PG8_SCHED;
;         }
	ds_read_b128 v[194:197], v157 offset:32768
	ds_read_b128 v[198:201], v157 offset:33792
	ds_read_b128 v[202:205], v157 offset:34816
	s_cmp_eq_u32 s57, 43
	s_cselect_b32 s28, s58, s28
	s_cselect_b32 s29, s59, s29
	s_add_i32 m0, s60, 0x2000
	s_nop 0
	global_load_lds_dwordx4 v134, s[28:29]
	ds_read_b128 v[206:209], v157 offset:35840
	ds_read_b128 v[210:213], v157 offset:36864
	ds_read_b128 v[214:217], v157 offset:37888
	s_add_u32 s30, s28, 0x58000
	s_addc_u32 s31, s29, 0
	s_add_i32 m0, s60, 0x3000
	s_nop 0
	global_load_lds_dwordx4 v134, s[30:31]
	ds_read_b128 v[218:221], v157 offset:38912
	ds_read_b128 v[222:225], v157 offset:39936
	ds_read_b128 v[158:161], v155 offset:32768
	s_add_u32 s30, s28, 0x160000
	s_addc_u32 s31, s29, 0
	s_add_i32 m0, s60, 0x6000
	s_nop 0
	global_load_lds_dwordx4 v134, s[30:31]
	ds_read_b128 v[162:165], v155 offset:33792
	ds_read_b128 v[166:169], v155 offset:34816
	ds_read_b128 v[174:177], v155 offset:35840
	s_add_u32 s30, s28, 0x1b8000
	s_addc_u32 s31, s29, 0
	s_add_i32 m0, s60, 0x7000
	s_nop 0
	global_load_lds_dwordx4 v134, s[30:31]
	ds_read_b128 v[178:181], v155 offset:49152
	ds_read_b128 v[182:185], v155 offset:50176
	ds_read_b128 v[186:189], v155 offset:51200
	s_add_u32 s34, s28, 0x80
	s_addc_u32 s35, s29, 0
	s_add_i32 m0, s60, 0x8000
	s_nop 0
	global_load_lds_dwordx4 v130, s[34:35]
	ds_read_b128 v[190:193], v155 offset:52224
	ds_read_b128 v[226:229], v157 offset:49152
	ds_read_b128 v[230:233], v157 offset:50176
	s_add_u32 s30, s34, 0x58000
	s_addc_u32 s31, s35, 0
	s_add_i32 m0, s60, 0x9000
	s_nop 0
	global_load_lds_dwordx4 v130, s[30:31]
	ds_read_b128 v[234:237], v157 offset:51200
	ds_read_b128 v[238:241], v157 offset:52224
	ds_read_b128 v[242:245], v157 offset:53248
	s_add_u32 s30, s34, 0x160000
	s_addc_u32 s31, s35, 0
	s_add_i32 m0, s60, 0xc000
	s_nop 0
	global_load_lds_dwordx4 v130, s[30:31]
	ds_read_b128 v[246:249], v157 offset:54272
	ds_read_b128 v[250:253], v157 offset:55296
	ds_read_b128 v[142:145], v157 offset:56320
	s_add_u32 s30, s34, 0x1b8000
	s_addc_u32 s31, s35, 0
	s_add_i32 m0, s60, 0xd000
	s_nop 0
	global_load_lds_dwordx4 v130, s[30:31]
	s_add_u32 s28, s28, 0x80
	s_addc_u32 s29, s29, 0
	s_waitcnt vmcnt(8) lgkmcnt(0)
	s_barrier
	v_mfma_f32_16x16x32_bf16 v[126:129], v[158:161], v[194:197], v[126:129]
	v_mfma_f32_16x16x32_bf16 v[126:129], v[162:165], v[198:201], v[126:129]
	v_mfma_f32_16x16x32_bf16 v[122:125], v[174:177], v[198:201], v[122:125]
	v_mfma_f32_16x16x32_bf16 v[122:125], v[166:169], v[194:197], v[122:125]
	v_mfma_f32_16x16x32_bf16 v[114:117], v[178:181], v[194:197], v[114:117]
	v_mfma_f32_16x16x32_bf16 v[114:117], v[182:185], v[198:201], v[114:117]
	v_mfma_f32_16x16x32_bf16 v[106:109], v[190:193], v[198:201], v[106:109]
	v_mfma_f32_16x16x32_bf16 v[106:109], v[186:189], v[194:197], v[106:109]
	v_mfma_f32_16x16x32_bf16 v[90:93], v[186:189], v[202:205], v[90:93]
	v_mfma_f32_16x16x32_bf16 v[90:93], v[190:193], v[206:209], v[90:93]
	v_mfma_f32_16x16x32_bf16 v[98:101], v[182:185], v[206:209], v[98:101]
	v_mfma_f32_16x16x32_bf16 v[98:101], v[178:181], v[202:205], v[98:101]
	v_mfma_f32_16x16x32_bf16 v[110:113], v[166:169], v[202:205], v[110:113]
	v_mfma_f32_16x16x32_bf16 v[110:113], v[174:177], v[206:209], v[110:113]
	v_mfma_f32_16x16x32_bf16 v[118:121], v[162:165], v[206:209], v[118:121]
	v_mfma_f32_16x16x32_bf16 v[118:121], v[158:161], v[202:205], v[118:121]
	v_mfma_f32_16x16x32_bf16 v[102:105], v[158:161], v[210:213], v[102:105]
	v_mfma_f32_16x16x32_bf16 v[102:105], v[162:165], v[214:217], v[102:105]
	v_mfma_f32_16x16x32_bf16 v[94:97], v[174:177], v[214:217], v[94:97]
	v_mfma_f32_16x16x32_bf16 v[94:97], v[166:169], v[210:213], v[94:97]
	v_mfma_f32_16x16x32_bf16 v[82:85], v[178:181], v[210:213], v[82:85]
	v_mfma_f32_16x16x32_bf16 v[82:85], v[182:185], v[214:217], v[82:85]
	v_mfma_f32_16x16x32_bf16 v[74:77], v[190:193], v[214:217], v[74:77]
	v_mfma_f32_16x16x32_bf16 v[74:77], v[186:189], v[210:213], v[74:77]
	v_mfma_f32_16x16x32_bf16 v[66:69], v[186:189], v[218:221], v[66:69]
	v_mfma_f32_16x16x32_bf16 v[66:69], v[190:193], v[222:225], v[66:69]
	v_mfma_f32_16x16x32_bf16 v[70:73], v[182:185], v[222:225], v[70:73]
	v_mfma_f32_16x16x32_bf16 v[70:73], v[178:181], v[218:221], v[70:73]
	v_mfma_f32_16x16x32_bf16 v[78:81], v[166:169], v[218:221], v[78:81]
	v_mfma_f32_16x16x32_bf16 v[78:81], v[174:177], v[222:225], v[78:81]
	v_mfma_f32_16x16x32_bf16 v[86:89], v[162:165], v[222:225], v[86:89]
	v_mfma_f32_16x16x32_bf16 v[86:89], v[158:161], v[218:221], v[86:89]
	v_mfma_f32_16x16x32_bf16 v[62:65], v[158:161], v[226:229], v[62:65]
	v_mfma_f32_16x16x32_bf16 v[62:65], v[162:165], v[230:233], v[62:65]
	v_mfma_f32_16x16x32_bf16 v[58:61], v[174:177], v[230:233], v[58:61]
	v_mfma_f32_16x16x32_bf16 v[58:61], v[166:169], v[226:229], v[58:61]
	v_mfma_f32_16x16x32_bf16 v[50:53], v[178:181], v[226:229], v[50:53]
	v_mfma_f32_16x16x32_bf16 v[50:53], v[182:185], v[230:233], v[50:53]
	v_mfma_f32_16x16x32_bf16 v[42:45], v[190:193], v[230:233], v[42:45]
	v_mfma_f32_16x16x32_bf16 v[42:45], v[186:189], v[226:229], v[42:45]
	v_mfma_f32_16x16x32_bf16 v[26:29], v[186:189], v[234:237], v[26:29]
	v_mfma_f32_16x16x32_bf16 v[26:29], v[190:193], v[238:241], v[26:29]
	v_mfma_f32_16x16x32_bf16 v[34:37], v[182:185], v[238:241], v[34:37]
	v_mfma_f32_16x16x32_bf16 v[34:37], v[178:181], v[234:237], v[34:37]
	v_mfma_f32_16x16x32_bf16 v[46:49], v[166:169], v[234:237], v[46:49]
	v_mfma_f32_16x16x32_bf16 v[46:49], v[174:177], v[238:241], v[46:49]
	v_mfma_f32_16x16x32_bf16 v[54:57], v[162:165], v[238:241], v[54:57]
	v_mfma_f32_16x16x32_bf16 v[54:57], v[158:161], v[234:237], v[54:57]
	v_mfma_f32_16x16x32_bf16 v[38:41], v[158:161], v[242:245], v[38:41]
	v_mfma_f32_16x16x32_bf16 v[38:41], v[162:165], v[246:249], v[38:41]
	v_mfma_f32_16x16x32_bf16 v[30:33], v[174:177], v[246:249], v[30:33]
	v_mfma_f32_16x16x32_bf16 v[30:33], v[166:169], v[242:245], v[30:33]
	v_mfma_f32_16x16x32_bf16 v[18:21], v[178:181], v[242:245], v[18:21]
	v_mfma_f32_16x16x32_bf16 v[18:21], v[182:185], v[246:249], v[18:21]
	v_mfma_f32_16x16x32_bf16 v[10:13], v[190:193], v[246:249], v[10:13]
	v_mfma_f32_16x16x32_bf16 v[10:13], v[186:189], v[242:245], v[10:13]
	v_mfma_f32_16x16x32_bf16 v[2:5], v[186:189], v[250:253], v[2:5]
	v_mfma_f32_16x16x32_bf16 v[2:5], v[190:193], v[142:145], v[2:5]
	v_mfma_f32_16x16x32_bf16 v[6:9], v[182:185], v[142:145], v[6:9]
	v_mfma_f32_16x16x32_bf16 v[6:9], v[178:181], v[250:253], v[6:9]
	v_mfma_f32_16x16x32_bf16 v[14:17], v[166:169], v[250:253], v[14:17]
	v_mfma_f32_16x16x32_bf16 v[14:17], v[174:177], v[142:145], v[14:17]
	v_mfma_f32_16x16x32_bf16 v[22:25], v[162:165], v[142:145], v[22:25]
	v_mfma_f32_16x16x32_bf16 v[22:25], v[158:161], v[250:253], v[22:25]
	s_waitcnt vmcnt(0)
	s_barrier
	s_add_i32 s57, s57, 1
